# P1: hand-written lean EpiZ epilogue fast path (cvt+store only) for tiles without rope/q-scale/kv/conv work; on top of mlperm2
# speedup vs baseline: 1.0067x; 1.0067x over previous
;     __device__ __forceinline__ void operator()(const f32x4 (&acc)[2][2][4][2], const Unit& u, int wr, int wc, int fr, int fq) const {
;         const int pn = u.pn;
;         const bool do_rope = (pn < 6) && ((wc & 1) == 0);
;         const bool is_kv = (pn >= 3 && pn < 9);
;         const int kvsel = is_kv ? (pn - 3) / 3 : 0;
;         const int g = is_kv ? (pn - 3) % 3 : 0;
;         const int W = 128 << (2 * g);
;         const size_t okp = g == 0 ? O_KV128_P : (g == 1 ? O_KV512_P : O_KV2048_P);
;         const size_t oks = g == 0 ? O_KV128_S : (g == 1 ? O_KV512_S : O_KV2048_S);
;         const bool is_conv = (pn >= 9 && pn < 17);
;         const float sgn = fq == 0 ? -1.f : 1.f;
; #pragma unroll
;         for (int ai = 0; ai < 2; ++ai)
; #pragma unroll
;             for (int m = 0; m < 4; ++m) {
;                 const int row = u.pm * BM + ai * HALF + wr * 64 + m * 16 + fr;
;                 const bool isP = row < MP, isS = (row >= MP) && (row < MT);
;                 const int b = isP ? (row >> 12) : (row - MP);
;                 const int t = row & 4095;
;                 float cosv[8], sinv[8];
;                 if (do_rope) {
;                     const f32x4* cs = (const f32x4*)(rope + (size_t)(isP ? t : 4096) * 16);
; #pragma unroll
;                     for (int q = 0; q < 4; ++q) { const f32x4 c = cs[q]; cosv[2 * q] = c[0]; sinv[2 * q] = c[1]; cosv[2 * q + 1] = c[2]; sinv[2 * q + 1] = c[3]; }
;                 }
.LBB0_133:
	s_cmp_lt_i32 s48, 6
	v_readlane_b32 s12, v253, 27
	s_cselect_b64 s[10:11], -1, 0
	v_readlane_b32 s13, v253, 28
	s_lshl_b32 s14, s18, 8
	v_readlane_b32 s1, v253, 23
	s_and_b64 s[10:11], s[12:13], s[10:11]
	s_add_i32 s14, s14, s1
	v_or_b32_e32 v187, s14, v184
	s_cmp_gt_u32 s48, 16
	s_cbranch_scc1 .Lz_lean
	s_cmp_lt_u32 s48, 6
	s_cbranch_scc1 .Lz_orig
	s_cmp_eq_u32 s18, 64
	s_cbranch_scc1 .Lz_orig
	s_and_b32 s98, s18, 15
	s_mov_b32 s99, 15
	s_cmp_eq_u32 s48, 7
	s_cselect_b32 s99, 14, s99
	s_cmp_eq_u32 s48, 8
	s_cselect_b32 s99, 8, s99
	s_cmp_lt_u32 s98, s99
	s_cbranch_scc1 .Lz_lean
.Lz_orig:
	v_mov_b32_e32 v164, 0
	v_cndmask_b32_e64 v0, 0, 1, s[10:11]
	v_cmp_gt_i32_e64 s[46:47], s0, v187
	v_bitop3_b32 v142, s14, v181, v184 bitop3:0xc8
	v_cmp_ne_u32_e64 s[42:43], 1, v0
	s_andn2_b64 vcc, exec, s[10:11]
	v_mov_b32_e32 v165, 0
	v_mov_b32_e32 v4, 0
	v_mov_b32_e32 v5, v164
	v_mov_b32_e32 v166, v164
	v_mov_b32_e32 v167, v164
	v_mov_b32_e32 v8, v164
	v_mov_b32_e32 v9, v164
	v_mov_b32_e32 v0, 0
	v_mov_b32_e32 v1, 0
	v_mov_b32_e32 v2, 0
	v_mov_b32_e32 v3, v164
	v_mov_b32_e32 v50, v164
	v_mov_b32_e32 v51, v164
	v_mov_b32_e32 v6, v164
	v_mov_b32_e32 v7, v164
	s_cbranch_vccnz .LBB0_135
	v_lshlrev_b32_e32 v0, 4, v142
	v_cndmask_b32_e64 v0, v182, v0, s[46:47]
	v_lshlrev_b32_e32 v4, 2, v0
	global_load_dwordx4 v[0:3], v4, s[34:35]
	global_load_dwordx4 v[168:171], v4, s[34:35] offset:16
	global_load_dwordx4 v[50:53], v4, s[34:35] offset:32
	global_load_dwordx4 v[172:175], v4, s[34:35] offset:48
	s_waitcnt vmcnt(0)
	v_mov_b32_e32 v164, v1
	v_mov_b32_e32 v165, v3
	v_mov_b32_e32 v4, v169
	v_mov_b32_e32 v5, v171
	v_mov_b32_e32 v166, v51
	v_mov_b32_e32 v167, v53
	v_mov_b32_e32 v8, v173
	v_mov_b32_e32 v9, v175
	v_mov_b32_e32 v1, v2
	v_mov_b32_e32 v2, v168
	v_mov_b32_e32 v3, v170
	v_mov_b32_e32 v51, v52
	v_mov_b32_e32 v6, v172
	v_mov_b32_e32 v7, v174

; __device__ __forceinline__ unsigned cvt_pk_bf16(float lo, float hi) { unsigned r; asm volatile("v_cvt_pk_bf16_f32 %0, %1, %2" : "=v"(r) : "v"(lo), "v"(hi)); return r; }
;     __device__ __forceinline__ void operator()(const f32x4 (&acc)[2][2][4][2], const Unit& u, int wr, int wc, int fr, int fq) const {
;     ...
; #pragma unroll
;         for (int ai = 0; ai < 2; ++ai)
; #pragma unroll
;             for (int m = 0; m < 4; ++m) {
;                 const int row = u.pm * BM + ai * HALF + wr * 64 + m * 16 + fr;
;                 const bool isP = row < MP, isS = (row >= MP) && (row < MT);
;                 const int b = isP ? (row >> 12) : (row - MP);
;                 const int t = row & 4095;
;                 float cosv[8], sinv[8];
;                 if (do_rope) {
;                     const f32x4* cs = (const f32x4*)(rope + (size_t)(isP ? t : 4096) * 16);
; #pragma unroll
;                     for (int q = 0; q < 4; ++q) { const f32x4 c = cs[q]; cosv[2 * q] = c[0]; sinv[2 * q] = c[1]; cosv[2 * q + 1] = c[2]; sinv[2 * q + 1] = c[3]; }
;                 }
; #pragma unroll
;                 for (int bj = 0; bj < 2; ++bj) {
;                     f32x4 v0 = acc[ai][bj][m][0], v1 = acc[ai][bj][m][1];
;                     const int cit = bj * HALF + wc * 32 + fq * 8;
;                     if (do_rope) {
; #pragma unroll
;                         for (int j = 0; j < 4; ++j) {
;                             const float p0 = __shfl_xor(v0[j], 16), p1 = __shfl_xor(v1[j], 16);
;                             const float r0 = v0[j] * cosv[j] + sgn * p0 * sinv[j], r1 = v1[j] * cosv[4 + j] + sgn * p1 * sinv[4 + j];
;                             v0[j] = fq < 2 ? r0 : v0[j]; v1[j] = fq < 2 ? r1 : v1[j];
;                         }
;                     }
;                     if (pn < 3) { v0 = v0 * QSCALE; v1 = v1 * QSCALE; }
;                     u32x4 w; w.x = cvt_pk_bf16(v0[0], v0[1]); w.y = cvt_pk_bf16(v0[2], v0[3]); w.z = cvt_pk_bf16(v1[0], v1[1]); w.w = cvt_pk_bf16(v1[2], v1[3]);
;                     *(u32x4*)(Z + (size_t)row * NZ + pn * BM + cit) = w;
.Lz_lean:
	s_lshl_b32 s98, s48, 9
	v_lshlrev_b32_e32 v164, 1, v158
	v_add_u32_e32 v164, s98, v164
	v_mov_b32_e32 v165, 0
	s_movk_i32 s99, 0x4200
	v_mad_u64_u32 v[166:167], vcc, v187, s99, v[164:165]
	v_lshl_add_u64 v[166:167], s[2:3], 0, v[166:167]
	v_cvt_pk_bf16_f32 v196, v134, v135
	v_cvt_pk_bf16_f32 v197, v136, v137
	v_cvt_pk_bf16_f32 v198, v138, v139
	v_cvt_pk_bf16_f32 v199, v140, v141
	global_store_dwordx4 v[166:167], v[196:199], off
	v_cvt_pk_bf16_f32 v200, v126, v127
	v_cvt_pk_bf16_f32 v201, v128, v129
	v_cvt_pk_bf16_f32 v202, v130, v131
	v_cvt_pk_bf16_f32 v203, v132, v133
	global_store_dwordx4 v[166:167], v[200:203], off offset:256
	s_mov_b32 vcc_lo, 0x42000
	s_mov_b32 vcc_hi, 0
	v_lshl_add_u64 v[168:169], v[166:167], 0, vcc
	v_cvt_pk_bf16_f32 v204, v118, v119
	v_cvt_pk_bf16_f32 v205, v120, v121
	v_cvt_pk_bf16_f32 v206, v122, v123
	v_cvt_pk_bf16_f32 v207, v124, v125
	global_store_dwordx4 v[168:169], v[204:207], off
	v_cvt_pk_bf16_f32 v208, v110, v111
	v_cvt_pk_bf16_f32 v209, v112, v113
	v_cvt_pk_bf16_f32 v210, v114, v115
	v_cvt_pk_bf16_f32 v211, v116, v117
	global_store_dwordx4 v[168:169], v[208:211], off offset:256
	s_mov_b32 vcc_lo, 0x84000
	s_mov_b32 vcc_hi, 0
	v_lshl_add_u64 v[168:169], v[166:167], 0, vcc
	v_cvt_pk_bf16_f32 v196, v106, v107
	v_cvt_pk_bf16_f32 v197, v108, v109
	v_cvt_pk_bf16_f32 v198, v102, v103
	v_cvt_pk_bf16_f32 v199, v104, v105
	global_store_dwordx4 v[168:169], v[196:199], off
	v_cvt_pk_bf16_f32 v200, v98, v99
	v_cvt_pk_bf16_f32 v201, v100, v101
	v_cvt_pk_bf16_f32 v202, v94, v95
	v_cvt_pk_bf16_f32 v203, v96, v97
	global_store_dwordx4 v[168:169], v[200:203], off offset:256
	s_mov_b32 vcc_lo, 0xc6000
	s_mov_b32 vcc_hi, 0
	v_lshl_add_u64 v[168:169], v[166:167], 0, vcc
	v_cvt_pk_bf16_f32 v204, v86, v87
	v_cvt_pk_bf16_f32 v205, v88, v89
	v_cvt_pk_bf16_f32 v206, v90, v91
	v_cvt_pk_bf16_f32 v207, v92, v93
	global_store_dwordx4 v[168:169], v[204:207], off
	v_cvt_pk_bf16_f32 v208, v78, v79
	v_cvt_pk_bf16_f32 v209, v80, v81
	v_cvt_pk_bf16_f32 v210, v82, v83
	v_cvt_pk_bf16_f32 v211, v84, v85
	global_store_dwordx4 v[168:169], v[208:211], off offset:256
	s_mov_b32 vcc_lo, 0x210000
	s_mov_b32 vcc_hi, 0
	v_lshl_add_u64 v[168:169], v[166:167], 0, vcc
	v_cvt_pk_bf16_f32 v196, v70, v71
	v_cvt_pk_bf16_f32 v197, v72, v73
	v_cvt_pk_bf16_f32 v198, v74, v75
	v_cvt_pk_bf16_f32 v199, v76, v77
	global_store_dwordx4 v[168:169], v[196:199], off
	v_cvt_pk_bf16_f32 v200, v62, v63
	v_cvt_pk_bf16_f32 v201, v64, v65
	v_cvt_pk_bf16_f32 v202, v66, v67
	v_cvt_pk_bf16_f32 v203, v68, v69
	global_store_dwordx4 v[168:169], v[200:203], off offset:256
	s_mov_b32 vcc_lo, 0x252000
	s_mov_b32 vcc_hi, 0
	v_lshl_add_u64 v[168:169], v[166:167], 0, vcc
	v_cvt_pk_bf16_f32 v204, v54, v55
	v_cvt_pk_bf16_f32 v205, v56, v57
	v_cvt_pk_bf16_f32 v206, v58, v59
	v_cvt_pk_bf16_f32 v207, v60, v61
	global_store_dwordx4 v[168:169], v[204:207], off
	v_cvt_pk_bf16_f32 v208, v42, v43
	v_cvt_pk_bf16_f32 v209, v44, v45
	v_cvt_pk_bf16_f32 v210, v46, v47
	v_cvt_pk_bf16_f32 v211, v48, v49
	global_store_dwordx4 v[168:169], v[208:211], off offset:256
	s_mov_b32 vcc_lo, 0x294000
	s_mov_b32 vcc_hi, 0
	v_lshl_add_u64 v[168:169], v[166:167], 0, vcc
	v_cvt_pk_bf16_f32 v196, v38, v39
	v_cvt_pk_bf16_f32 v197, v40, v41
	v_cvt_pk_bf16_f32 v198, v34, v35
	v_cvt_pk_bf16_f32 v199, v36, v37
	global_store_dwordx4 v[168:169], v[196:199], off
	v_cvt_pk_bf16_f32 v200, v30, v31
	v_cvt_pk_bf16_f32 v201, v32, v33
	v_cvt_pk_bf16_f32 v202, v26, v27
	v_cvt_pk_bf16_f32 v203, v28, v29
	global_store_dwordx4 v[168:169], v[200:203], off offset:256
	s_mov_b32 vcc_lo, 0x2d6000
	s_mov_b32 vcc_hi, 0
	v_lshl_add_u64 v[168:169], v[166:167], 0, vcc
	v_cvt_pk_bf16_f32 v204, v18, v19
	v_cvt_pk_bf16_f32 v205, v20, v21
	v_cvt_pk_bf16_f32 v206, v22, v23
	v_cvt_pk_bf16_f32 v207, v24, v25
	global_store_dwordx4 v[168:169], v[204:207], off
	v_cvt_pk_bf16_f32 v208, v14, v15
	v_cvt_pk_bf16_f32 v209, v16, v17
	v_cvt_pk_bf16_f32 v210, v10, v11
	v_cvt_pk_bf16_f32 v211, v12, v13
	global_store_dwordx4 v[168:169], v[208:211], off offset:256
	s_branch .LBB0_297
